# v23 + P13 EpiFinal phase 1: dummy loads touch the x lines of row groups 1..7 up front
# baseline (speedup 1.0000x reference)
.LBB0_3464:
	v_lshlrev_b32_e32 v130, 3, v153
	s_lshl_b32 s3, s10, 8
	s_lshl_b32 s4, s53, 8
	v_lshl_or_b32 v130, s11, 5, v130
	v_or_b32_e32 v132, s4, v130
	v_add_u32_e32 v130, s3, v1
	v_ashrrev_i32_e32 v131, 31, v130
	v_lshlrev_b64 v[130:131], 12, v[130:131]
	v_lshl_add_u64 v[130:131], s[26:27], 0, v[130:131]
	v_ashrrev_i32_e32 v133, 31, v132
	v_lshl_add_u64 v[130:131], v[132:133], 2, v[130:131]
	s_waitcnt vmcnt(0)
	s_barrier
	global_load_dwordx4 v[134:137], v[130:131], off
	global_load_dwordx4 v[142:145], v[130:131], off offset:16
	global_load_dwordx4 v[146:149], v[130:131], off offset:512
	global_load_dwordx4 v[154:157], v[130:131], off offset:528
	s_mov_b32 s47, 0
	s_mov_b32 s46, 0x10000
	v_lshl_add_u64 v[200:201], v[130:131], 0, s[46:47]
	global_load_dword v236, v[200:201], off
	global_load_dword v236, v[200:201], off offset:512
	s_mov_b32 s46, 0x20000
	v_lshl_add_u64 v[202:203], v[130:131], 0, s[46:47]
	global_load_dword v236, v[202:203], off
	global_load_dword v236, v[202:203], off offset:512
	s_mov_b32 s46, 0x30000
	v_lshl_add_u64 v[204:205], v[130:131], 0, s[46:47]
	global_load_dword v236, v[204:205], off
	global_load_dword v236, v[204:205], off offset:512
	s_mov_b32 s46, 0x80000
	v_lshl_add_u64 v[206:207], v[130:131], 0, s[46:47]
	global_load_dword v236, v[206:207], off
	global_load_dword v236, v[206:207], off offset:512
	s_mov_b32 s46, 0x90000
	v_lshl_add_u64 v[208:209], v[130:131], 0, s[46:47]
	global_load_dword v236, v[208:209], off
	global_load_dword v236, v[208:209], off offset:512
	s_mov_b32 s46, 0xa0000
	v_lshl_add_u64 v[210:211], v[130:131], 0, s[46:47]
	global_load_dword v236, v[210:211], off
	global_load_dword v236, v[210:211], off offset:512
	s_mov_b32 s46, 0xb0000
	v_lshl_add_u64 v[212:213], v[130:131], 0, s[46:47]
	global_load_dword v236, v[212:213], off
	global_load_dword v236, v[212:213], off offset:512
	v_mbcnt_lo_u32_b32 v138, -1, 0
	v_mbcnt_hi_u32_b32 v138, -1, v138
	v_and_b32_e32 v150, 64, v138
	v_xor_b32_e32 v139, 16, v138
	v_add_u32_e32 v151, 64, v150
	v_cmp_lt_i32_e32 vcc, v139, v151
	s_lshl_b32 s0, s11, 2
	s_add_i32 s5, s0, 0
	v_cndmask_b32_e32 v139, v138, v139, vcc
	v_lshlrev_b32_e32 v150, 2, v139
	s_waitcnt vmcnt(14)
	v_pk_fma_f32 v[128:129], v[128:129], 0.5, v[136:137] op_sel_hi:[1,0,1]
	v_pk_fma_f32 v[134:135], v[126:127], 0.5, v[134:135] op_sel_hi:[1,0,1]
	v_pk_fma_f32 v[124:125], v[124:125], 0.5, v[144:145] op_sel_hi:[1,0,1]
	v_pk_fma_f32 v[126:127], v[122:123], 0.5, v[142:143] op_sel_hi:[1,0,1]
	v_pk_fma_f32 v[120:121], v[120:121], 0.5, v[148:149] op_sel_hi:[1,0,1]
	v_pk_fma_f32 v[122:123], v[118:119], 0.5, v[146:147] op_sel_hi:[1,0,1]
	v_pk_fma_f32 v[116:117], v[116:117], 0.5, v[156:157] op_sel_hi:[1,0,1]
	v_pk_fma_f32 v[118:119], v[114:115], 0.5, v[154:155] op_sel_hi:[1,0,1]
	v_mul_f32_e32 v114, v135, v135
	v_mul_f32_e32 v115, v129, v129
	v_mul_f32_e32 v136, v127, v127
	v_mul_f32_e32 v137, v125, v125
	v_mul_f32_e32 v139, v123, v123
	v_mul_f32_e32 v142, v121, v121
	v_mul_f32_e32 v143, v119, v119
	v_mul_f32_e32 v144, v117, v117
	v_fmac_f32_e32 v114, v134, v134
	v_fmac_f32_e32 v115, v128, v128
	v_fmac_f32_e32 v136, v126, v126
	v_fmac_f32_e32 v137, v124, v124
	v_fmac_f32_e32 v139, v122, v122
	v_fmac_f32_e32 v142, v120, v120
	v_fmac_f32_e32 v143, v118, v118
	v_fmac_f32_e32 v144, v116, v116
	v_add_f32_e32 v114, v114, v115
	v_add_f32_e32 v115, v136, v137
	v_add_f32_e32 v136, v139, v142
	v_add_f32_e32 v137, v143, v144
	v_add_f32_e32 v114, v114, v115
	v_add_f32_e32 v115, v136, v137
	v_add_f32_e32 v114, v114, v115
	ds_bpermute_b32 v115, v150, v114
	v_xor_b32_e32 v136, 32, v138
	v_cmp_lt_i32_e32 vcc, v136, v151
	s_waitcnt lgkmcnt(0)
	v_add_f32_e32 v114, v114, v115
	v_cndmask_b32_e32 v136, v138, v136, vcc
	v_lshlrev_b32_e32 v151, 2, v136
	ds_bpermute_b32 v115, v151, v114
	v_cmp_eq_u32_e32 vcc, 0, v153
	s_and_saveexec_b64 s[0:1], vcc
	s_cbranch_execz .LBB0_3466
	v_lshl_add_u32 v136, v1, 4, s5
	s_waitcnt lgkmcnt(0)
	v_add_f32_e32 v114, v114, v115
	ds_write_b32 v136, v114
